# attention loops: v_pk_add_f32 split into scalar v_add_f32 pairs, zero-plus-x row-sum seeds removed (on top of v4)
# speedup vs baseline: 1.0309x; 1.0067x over previous
.LBB0_577:
	v_exp_f32_e32 v219, v144
	v_exp_f32_e32 v225, v145
	v_exp_f32_e32 v227, v146
	v_exp_f32_e32 v248, v147
	ds_read_b128 v[144:147], v208 offset:36864
	v_exp_f32_e32 v240, v148
	v_exp_f32_e32 v242, v149
	v_exp_f32_e32 v244, v150
	v_exp_f32_e32 v246, v151
	v_cvt_pk_bf16_f32 v148, v219, v225
	v_cvt_pk_bf16_f32 v149, v227, v248
	v_cvt_pk_bf16_f32 v150, v240, v242
	v_cvt_pk_bf16_f32 v151, v244, v246
	ds_read_b128 v[228:231], v208 offset:36896
	ds_read_b128 v[232:235], v208 offset:41472
	s_waitcnt lgkmcnt(2)
	v_mfma_f32_32x32x16_bf16 v[64:79], v[144:147], v[148:151], v[64:79]
	v_add_f32_e32 v128, v129, v128
	v_add_f32_e32 v129, v161, v160
	ds_read_b128 v[144:147], v208 offset:46080
	ds_read_b128 v[236:239], v208 offset:41504
	v_add_f32_e32 v128, v130, v128
	v_add_f32_e32 v129, v162, v129
	v_add_f32_e32 v128, v131, v128
	v_add_f32_e32 v129, v163, v129
	s_waitcnt lgkmcnt(2)
	v_mfma_f32_32x32x16_bf16 v[48:63], v[232:235], v[148:151], v[48:63]
	v_add_f32_e32 v132, v132, v128
	v_add_f32_e32 v233, v164, v129
	ds_read_b128 v[128:131], v208 offset:50688
	ds_read_b128 v[160:163], v208 offset:46112
	v_exp_f32_e32 v152, v152
	v_exp_f32_e32 v164, v153
	v_exp_f32_e32 v154, v154
	v_exp_f32_e32 v232, v155
	s_waitcnt lgkmcnt(3)
	v_mfma_f32_32x32x16_bf16 v[32:47], v[144:147], v[148:151], v[32:47]
	v_exp_f32_e32 v156, v156
	ds_read_b128 v[144:147], v208 offset:50720
	v_add_f32_e32 v132, v133, v132
	v_add_f32_e32 v133, v165, v233
	v_add_f32_e32 v133, v166, v133
	v_exp_f32_e32 v166, v112
	v_add_f32_e32 v132, v134, v132
	s_waitcnt lgkmcnt(2)
	v_mfma_f32_32x32x16_bf16 v[0:15], v[128:131], v[148:151], v[0:15]
	v_exp_f32_e32 v148, v157
	v_exp_f32_e32 v150, v158
	v_exp_f32_e32 v158, v159
	v_cvt_pk_bf16_f32 v128, v152, v164
	v_cvt_pk_bf16_f32 v129, v154, v232
	v_cvt_pk_bf16_f32 v130, v156, v148
	v_cvt_pk_bf16_f32 v131, v150, v158
	v_add_f32_e32 v132, v135, v132
	v_add_f32_e32 v133, v167, v133
	s_waitcnt lgkmcnt(1)
	v_mfma_f32_32x32x16_bf16 v[32:47], v[160:163], v[128:131], v[32:47]
	v_exp_f32_e32 v160, v113
	v_exp_f32_e32 v161, v114
	v_exp_f32_e32 v162, v115
	ds_read_b128 v[112:115], v208 offset:36928
	v_add_f32_e32 v132, v136, v132
	v_add_f32_e32 v133, v168, v133
	v_exp_f32_e32 v241, v116
	v_mfma_f32_32x32x16_bf16 v[64:79], v[228:231], v[128:131], v[64:79]
	v_exp_f32_e32 v243, v117
	v_exp_f32_e32 v245, v118
	v_exp_f32_e32 v247, v119
	v_add_f32_e32 v132, v137, v132
	v_add_f32_e32 v133, v169, v133
	v_add_f32_e32 v132, v138, v132
	v_add_f32_e32 v133, v170, v133
	v_mfma_f32_32x32x16_bf16 v[48:63], v[236:239], v[128:131], v[48:63]
	v_add_f32_e32 v136, v139, v132
	v_add_f32_e32 v137, v171, v133
	v_cvt_pk_bf16_f32 v116, v166, v160
	v_cvt_pk_bf16_f32 v117, v161, v162
	v_cvt_pk_bf16_f32 v118, v241, v243
	v_cvt_pk_bf16_f32 v119, v245, v247
	v_exp_f32_e32 v153, v120
	s_waitcnt lgkmcnt(1)
	v_mfma_f32_32x32x16_bf16 v[0:15], v[144:147], v[128:131], v[0:15]
	ds_read_b128 v[128:131], v208 offset:41536
	ds_read_b128 v[132:135], v208 offset:36960
	v_exp_f32_e32 v165, v121
	v_add_f32_e32 v120, v225, v219
	v_add_f32_e32 v121, v160, v166
	v_add_f32_e32 v120, v227, v120
	s_waitcnt lgkmcnt(2)
	v_mfma_f32_32x32x16_bf16 v[64:79], v[112:115], v[116:119], v[64:79]
	v_add_f32_e32 v112, v140, v136
	v_add_f32_e32 v113, v172, v137
	v_add_f32_e32 v112, v141, v112
	v_add_f32_e32 v140, v173, v113
	v_add_f32_e32 v141, v142, v112
	ds_read_b128 v[112:115], v208 offset:46144
	ds_read_b128 v[136:139], v208 offset:41568
	v_add_f32_e32 v121, v161, v121
	s_waitcnt lgkmcnt(3)
	v_mfma_f32_32x32x16_bf16 v[48:63], v[128:131], v[116:119], v[48:63]
	v_add_f32_e32 v128, v174, v140
	v_add_f32_e32 v129, v143, v141
	v_add_f32_e32 v128, v175, v128
	v_add_f32_e32 v128, v129, v128
	v_add_f32_e32 v144, v218, v128
	ds_read_b128 v[128:131], v208 offset:50752
	ds_read_b128 v[140:143], v208 offset:46176
	v_add_f32_e32 v120, v248, v120
	s_waitcnt lgkmcnt(3)
	v_mfma_f32_32x32x16_bf16 v[32:47], v[112:115], v[116:119], v[32:47]
	ds_read_b128 v[112:115], v208 offset:50784
	v_add_f32_e32 v121, v162, v121
	v_add_f32_e64 v120, v240, v120
	v_add_f32_e64 v121, v241, v121
	v_exp_f32_e32 v155, v122
	v_exp_f32_e32 v233, v123
	v_exp_f32_e32 v157, v124
	v_exp_f32_e32 v149, v125
	s_waitcnt lgkmcnt(2)
	v_mfma_f32_32x32x16_bf16 v[0:15], v[128:131], v[116:119], v[0:15]
	v_exp_f32_e32 v151, v126
	v_exp_f32_e32 v159, v127
	v_add_f32_e32 v120, v242, v120
	v_add_f32_e32 v121, v243, v121
	v_cvt_pk_bf16_f32 v116, v153, v165
	v_add_f32_e32 v120, v244, v120
	v_add_f32_e32 v121, v245, v121
	v_cvt_pk_bf16_f32 v117, v155, v233
	v_add_f32_e32 v120, v246, v120
	v_add_f32_e32 v121, v247, v121
	v_cvt_pk_bf16_f32 v118, v157, v149
	v_add_f32_e32 v120, v152, v120
	v_add_f32_e32 v121, v153, v121
	v_cvt_pk_bf16_f32 v119, v151, v159
	v_add_f32_e32 v120, v164, v120
	v_add_f32_e32 v121, v165, v121
	s_add_i32 s53, s53, 2
	v_mfma_f32_32x32x16_bf16 v[64:79], v[132:135], v[116:119], v[64:79]
	v_add_f32_e64 v120, v154, v120
	v_add_f32_e64 v121, v155, v121
	s_addk_i32 s52, 0x2000
	v_add_f32_e64 v120, v232, v120
	v_add_f32_e64 v121, v233, v121
	s_andn2_b64 vcc, exec, s[16:17]
	v_add_f32_e32 v120, v156, v120
	v_add_f32_e32 v121, v157, v121
	s_addk_i32 s51, 0x80
	v_add_f32_e32 v120, v148, v120
	v_add_f32_e32 v121, v149, v121
	v_mfma_f32_32x32x16_bf16 v[48:63], v[136:139], v[116:119], v[48:63]
	v_add_f32_e64 v120, v150, v120
	v_add_f32_e64 v121, v151, v121
	v_add_f32_e64 v120, v158, v120
	v_add_f32_e64 v121, v159, v121
	v_add_f32_e32 v120, v120, v121
	v_add_f32_e32 v218, v144, v120
	s_waitcnt lgkmcnt(1)
	v_mfma_f32_32x32x16_bf16 v[32:47], v[140:143], v[116:119], v[32:47]
	s_waitcnt lgkmcnt(0)
	v_mfma_f32_32x32x16_bf16 v[0:15], v[112:115], v[116:119], v[0:15]
	s_cbranch_vccz .LBB0_594

.LBB0_596:
	v_exp_f32_e32 v227, v144
	v_exp_f32_e32 v248, v145
	v_exp_f32_e32 v249, v146
	v_exp_f32_e32 v250, v147
	ds_read_b128 v[144:147], v208 offset:36864
	v_exp_f32_e32 v240, v148
	v_exp_f32_e32 v242, v149
	v_exp_f32_e32 v244, v150
	v_exp_f32_e32 v246, v151
	v_cvt_pk_bf16_f32 v148, v227, v248
	v_cvt_pk_bf16_f32 v149, v249, v250
	v_cvt_pk_bf16_f32 v150, v240, v242
	v_cvt_pk_bf16_f32 v151, v244, v246
	ds_read_b128 v[228:231], v208 offset:36896
	ds_read_b128 v[232:235], v208 offset:41472
	s_waitcnt lgkmcnt(2)
	v_mfma_f32_32x32x16_bf16 v[0:15], v[144:147], v[148:151], v[0:15]
	v_add_f32_e32 v128, v129, v128
	v_add_f32_e32 v129, v161, v160
	ds_read_b128 v[144:147], v208 offset:46080
	ds_read_b128 v[236:239], v208 offset:41504
	v_add_f32_e32 v128, v130, v128
	v_add_f32_e32 v129, v162, v129
	v_add_f32_e32 v128, v131, v128
	v_add_f32_e32 v129, v163, v129
	s_waitcnt lgkmcnt(2)
	v_mfma_f32_32x32x16_bf16 v[48:63], v[232:235], v[148:151], v[48:63]
	v_add_f32_e32 v132, v132, v128
	v_add_f32_e32 v233, v164, v129
	ds_read_b128 v[128:131], v208 offset:50688
	ds_read_b128 v[160:163], v208 offset:46112
	v_exp_f32_e32 v152, v152
	v_exp_f32_e32 v164, v153
	v_exp_f32_e32 v154, v154
	v_exp_f32_e32 v232, v155
	s_waitcnt lgkmcnt(3)
	v_mfma_f32_32x32x16_bf16 v[32:47], v[144:147], v[148:151], v[32:47]
	v_exp_f32_e32 v156, v156
	ds_read_b128 v[144:147], v208 offset:50720
	v_add_f32_e32 v132, v133, v132
	v_add_f32_e32 v133, v165, v233
	v_add_f32_e32 v133, v166, v133
	v_exp_f32_e32 v166, v112
	v_add_f32_e32 v132, v134, v132
	s_waitcnt lgkmcnt(2)
	v_mfma_f32_32x32x16_bf16 v[16:31], v[128:131], v[148:151], v[16:31]
	v_exp_f32_e32 v148, v157
	v_exp_f32_e32 v150, v158
	v_exp_f32_e32 v158, v159
	v_cvt_pk_bf16_f32 v128, v152, v164
	v_cvt_pk_bf16_f32 v129, v154, v232
	v_cvt_pk_bf16_f32 v130, v156, v148
	v_cvt_pk_bf16_f32 v131, v150, v158
	v_add_f32_e32 v132, v135, v132
	v_add_f32_e32 v133, v167, v133
	s_waitcnt lgkmcnt(1)
	v_mfma_f32_32x32x16_bf16 v[32:47], v[160:163], v[128:131], v[32:47]
	v_exp_f32_e32 v160, v113
	v_exp_f32_e32 v161, v114
	v_exp_f32_e32 v162, v115
	ds_read_b128 v[112:115], v208 offset:36928
	v_add_f32_e32 v132, v136, v132
	v_add_f32_e32 v133, v168, v133
	v_exp_f32_e32 v241, v116
	v_mfma_f32_32x32x16_bf16 v[0:15], v[228:231], v[128:131], v[0:15]
	v_exp_f32_e32 v243, v117
	v_exp_f32_e32 v245, v118
	v_exp_f32_e32 v247, v119
	v_add_f32_e32 v132, v137, v132
	v_add_f32_e32 v133, v169, v133
	v_add_f32_e32 v132, v138, v132
	v_add_f32_e32 v133, v170, v133
	v_mfma_f32_32x32x16_bf16 v[48:63], v[236:239], v[128:131], v[48:63]
	v_add_f32_e32 v136, v139, v132
	v_add_f32_e32 v137, v171, v133
	v_cvt_pk_bf16_f32 v116, v166, v160
	v_cvt_pk_bf16_f32 v117, v161, v162
	v_cvt_pk_bf16_f32 v118, v241, v243
	v_cvt_pk_bf16_f32 v119, v245, v247
	v_exp_f32_e32 v153, v120
	s_waitcnt lgkmcnt(1)
	v_mfma_f32_32x32x16_bf16 v[16:31], v[144:147], v[128:131], v[16:31]
	ds_read_b128 v[128:131], v208 offset:41536
	ds_read_b128 v[132:135], v208 offset:36960
	v_exp_f32_e32 v165, v121
	v_add_f32_e32 v120, v248, v227
	v_add_f32_e32 v121, v160, v166
	v_add_f32_e32 v120, v249, v120
	s_waitcnt lgkmcnt(2)
	v_mfma_f32_32x32x16_bf16 v[0:15], v[112:115], v[116:119], v[0:15]
	v_add_f32_e32 v112, v140, v136
	v_add_f32_e32 v113, v172, v137
	v_add_f32_e32 v112, v141, v112
	v_add_f32_e32 v140, v173, v113
	v_add_f32_e32 v141, v142, v112
	ds_read_b128 v[112:115], v208 offset:46144
	ds_read_b128 v[136:139], v208 offset:41568
	v_add_f32_e32 v121, v161, v121
	s_waitcnt lgkmcnt(3)
	v_mfma_f32_32x32x16_bf16 v[48:63], v[128:131], v[116:119], v[48:63]
	v_add_f32_e32 v128, v174, v140
	v_add_f32_e32 v129, v143, v141
	v_add_f32_e32 v128, v175, v128
	v_add_f32_e32 v128, v129, v128
	v_add_f32_e32 v144, v213, v128
	ds_read_b128 v[128:131], v208 offset:50752
	ds_read_b128 v[140:143], v208 offset:46176
	v_add_f32_e32 v120, v250, v120
	s_waitcnt lgkmcnt(3)
	v_mfma_f32_32x32x16_bf16 v[32:47], v[112:115], v[116:119], v[32:47]
	ds_read_b128 v[112:115], v208 offset:50784
	v_add_f32_e32 v121, v162, v121
	v_add_f32_e64 v120, v240, v120
	v_add_f32_e64 v121, v241, v121
	v_exp_f32_e32 v155, v122
	v_exp_f32_e32 v233, v123
	v_exp_f32_e32 v157, v124
	v_exp_f32_e32 v149, v125
	s_waitcnt lgkmcnt(2)
	v_mfma_f32_32x32x16_bf16 v[16:31], v[128:131], v[116:119], v[16:31]
	v_exp_f32_e32 v151, v126
	v_exp_f32_e32 v159, v127
	v_add_f32_e32 v120, v242, v120
	v_add_f32_e32 v121, v243, v121
	v_cvt_pk_bf16_f32 v116, v153, v165
	v_add_f32_e32 v120, v244, v120
	v_add_f32_e32 v121, v245, v121
	v_cvt_pk_bf16_f32 v117, v155, v233
	v_add_f32_e32 v120, v246, v120
	v_add_f32_e32 v121, v247, v121
	v_cvt_pk_bf16_f32 v118, v157, v149
	v_add_f32_e32 v120, v152, v120
	v_add_f32_e32 v121, v153, v121
	v_cvt_pk_bf16_f32 v119, v151, v159
	v_add_f32_e32 v120, v164, v120
	v_add_f32_e32 v121, v165, v121
	s_add_i32 s18, s18, 2
	v_mfma_f32_32x32x16_bf16 v[0:15], v[132:135], v[116:119], v[0:15]
	v_add_f32_e64 v120, v154, v120
	v_add_f32_e64 v121, v155, v121
	s_addk_i32 s37, 0x2000
	v_add_f32_e64 v120, v232, v120
	v_add_f32_e64 v121, v233, v121
	s_andn2_b64 vcc, exec, s[12:13]
	v_add_f32_e32 v120, v156, v120
	v_add_f32_e32 v121, v157, v121
	s_addk_i32 s19, 0x80
	v_add_f32_e32 v120, v148, v120
	v_add_f32_e32 v121, v149, v121
	v_mfma_f32_32x32x16_bf16 v[48:63], v[136:139], v[116:119], v[48:63]
	v_add_f32_e64 v120, v150, v120
	v_add_f32_e64 v121, v151, v121
	v_add_f32_e64 v120, v158, v120
	v_add_f32_e64 v121, v159, v121
	v_add_f32_e32 v120, v120, v121
	v_add_f32_e32 v213, v144, v120
	s_waitcnt lgkmcnt(1)
	v_mfma_f32_32x32x16_bf16 v[32:47], v[140:143], v[116:119], v[32:47]
	s_waitcnt lgkmcnt(0)
	v_mfma_f32_32x32x16_bf16 v[16:31], v[112:115], v[116:119], v[16:31]
	s_cbranch_vccz .LBB0_574

; __device__ __forceinline__ unsigned pk2(float lo, float hi) { f32x2_t v = {lo, hi}; bf16x2_t b = __builtin_convertvector(v, bf16x2_t); return __builtin_bit_cast(unsigned, b); }
; __device__ __forceinline__ float fexp2(float x) { return __builtin_amdgcn_exp2f(x); }
; #define MFMA(a, b, c) __builtin_amdgcn_mfma_f32_32x32x16_bf16((a), (b), (c), 0, 0, 0)
; template <int DQK, int DV>
; __device__ __forceinline__ void attn_pass2(const bf16_t* __restrict__ qh, const bf16_t* __restrict__ kh, const bf16_t* __restrict__ vth, int q0, char* smem, f32x16 (&o)[2][DV / 32], float kmax, int wvp) {
;     ...
;     const char* kb0 = sK + cur * KSB + kofs;
; #pragma unroll
;     for (int ks = 0; ks < NKS; ++ks) {
;       const bf16x8 a0 = *(const bf16x8*)(kb0 + ks * 32), a1 = *(const bf16x8*)(kb0 + 32 * KP + ks * 32);
; #pragma unroll
;       for (int qb = 0; qb < 2; ++qb) {
;         if (ks == 0) {
;           f32x16 z;
; #pragma unroll
;           for (int i = 0; i < 16; ++i) z[i] = 0.f;
;           s[qb][0] = MFMA(a0, qf[qb][0], z); s[qb][1] = MFMA(a1, qf[qb][0], z);
;         } else { s[qb][0] = MFMA(a0, qf[qb][ks], s[qb][0]); s[qb][1] = MFMA(a1, qf[qb][ks], s[qb][1]); }
;       }
;     }
;     __builtin_amdgcn_sched_barrier(0);
; #pragma unroll
;     for (int qb = 0; qb < 2; ++qb) {
;       float rs0 = 0.f, rs1 = 0.f;
; #pragma unroll
;       for (int i = 0; i < 16; ++i) { s[qb][0][i] = fexp2(s[qb][0][i] - mref[qb]); s[qb][1][i] = fexp2(s[qb][1][i] - mref[qb]); rs0 += s[qb][0][i]; rs1 += s[qb][1][i]; }
;       l_run[qb] += rs0 + rs1;
;     }
;     const char* vb0 = sV + cur * VSB + vofs;
; #pragma unroll
;     for (int kb = 0; kb < 2; ++kb)
; #pragma unroll
;       for (int s2 = 0; s2 < 2; ++s2) {
;         bf16x8 pq[2];
; #pragma unroll
;         for (int qb = 0; qb < 2; ++qb) {
;           u32x4 w;
;           w.x = pk2(s[qb][kb][8 * s2 + 0], s[qb][kb][8 * s2 + 1]); w.y = pk2(s[qb][kb][8 * s2 + 2], s[qb][kb][8 * s2 + 3]);
;           w.z = pk2(s[qb][kb][8 * s2 + 4], s[qb][kb][8 * s2 + 5]); w.w = pk2(s[qb][kb][8 * s2 + 6], s[qb][kb][8 * s2 + 7]);
;           pq[qb] = __builtin_bit_cast(bf16x8, w);
;         }
; #pragma unroll
;         for (int eb = 0; eb < NEB; ++eb) {
;           const bf16x8 a = *(const bf16x8*)(vb0 + eb * 32 * VP + (32 * kb + 16 * s2) * 2);
.LBB0_1429:
	s_mulk_i32 s7, 0x2400
	v_add_u32_e32 v180, s7, v169
	ds_read_b128 v[64:67], v180
	ds_read_b128 v[176:179], v180 offset:32
	ds_read_b128 v[68:71], v180 offset:4608
	ds_read_b128 v[192:195], v180 offset:4640
	s_add_i32 s6, s6, 1
	s_waitcnt lgkmcnt(3)
	v_mfma_f32_32x32x16_bf16 v[112:127], v[64:67], v[128:131], v[236:251]
	s_waitcnt lgkmcnt(1)
	v_mfma_f32_32x32x16_bf16 v[96:111], v[68:71], v[128:131], v[236:251]
	v_mfma_f32_32x32x16_bf16 v[80:95], v[64:67], v[144:147], v[236:251]
	v_mfma_f32_32x32x16_bf16 v[64:79], v[68:71], v[144:147], v[236:251]
	v_mfma_f32_32x32x16_bf16 v[112:127], v[176:179], v[132:135], v[112:127]
	s_waitcnt lgkmcnt(0)
	v_mfma_f32_32x32x16_bf16 v[96:111], v[192:195], v[132:135], v[96:111]
	v_mfma_f32_32x32x16_bf16 v[80:95], v[176:179], v[148:151], v[80:95]
	v_mfma_f32_32x32x16_bf16 v[64:79], v[192:195], v[148:151], v[64:79]
	ds_read_b128 v[176:179], v180 offset:64
	ds_read_b128 v[192:195], v180 offset:96
	ds_read_b128 v[196:199], v180 offset:4672
	ds_read_b128 v[200:203], v180 offset:4704
	s_waitcnt lgkmcnt(3)
	v_mfma_f32_32x32x16_bf16 v[112:127], v[176:179], v[136:139], v[112:127]
	s_waitcnt lgkmcnt(1)
	v_mfma_f32_32x32x16_bf16 v[96:111], v[196:199], v[136:139], v[96:111]
	v_mfma_f32_32x32x16_bf16 v[80:95], v[176:179], v[152:155], v[80:95]
	v_mfma_f32_32x32x16_bf16 v[64:79], v[196:199], v[152:155], v[64:79]
	v_mfma_f32_32x32x16_bf16 v[112:127], v[192:195], v[140:143], v[112:127]
	s_waitcnt lgkmcnt(0)
	v_mfma_f32_32x32x16_bf16 v[96:111], v[200:203], v[140:143], v[96:111]
	v_mfma_f32_32x32x16_bf16 v[80:95], v[192:195], v[156:159], v[80:95]
	v_mfma_f32_32x32x16_bf16 v[64:79], v[200:203], v[156:159], v[64:79]
	s_nop 9
	v_exp_f32_e32 v186, v96
	v_exp_f32_e32 v97, v97
	v_exp_f32_e32 v177, v112
	v_exp_f32_e32 v113, v113
	v_exp_f32_e32 v179, v114
	v_exp_f32_e32 v187, v98
	v_add_f32_e32 v98, v97, v186
	v_exp_f32_e32 v115, v115
	v_exp_f32_e32 v190, v99
	v_exp_f32_e32 v204, v100
	v_exp_f32_e32 v99, v116
	v_exp_f32_e32 v117, v117
	v_add_f32_e32 v96, v113, v177
	v_exp_f32_e32 v101, v101
	v_add_f32_e32 v96, v179, v96
	v_exp_f32_e32 v181, v118
	v_add_f32_e32 v96, v115, v96
	v_add_f32_e32 v96, v99, v96
	v_add_f32_e32 v96, v117, v96
	v_add_f32_e32 v112, v181, v96
	v_exp_f32_e32 v176, v119
	v_exp_f32_e32 v178, v103
	v_add_f32_e32 v98, v187, v98
	v_exp_f32_e32 v205, v102
	v_exp_f32_e32 v180, v120
	v_exp_f32_e32 v96, v104
	v_exp_f32_e32 v104, v123
	v_add_f32_e32 v98, v190, v98
	v_exp_f32_e32 v100, v106
	v_exp_f32_e32 v106, v107
	v_add_f32_e32 v98, v204, v98
	v_exp_f32_e32 v118, v124
	v_add_f32_e32 v98, v101, v98
	v_exp_f32_e32 v120, v108
	v_add_f32_e32 v102, v205, v98
	v_exp_f32_e32 v124, v125
	v_exp_f32_e32 v116, v121
	v_exp_f32_e32 v108, v109
	v_exp_f32_e32 v114, v105
	v_exp_f32_e32 v98, v122
	v_exp_f32_e32 v122, v126
	v_exp_f32_e32 v110, v110
	v_exp_f32_e32 v126, v127
	v_exp_f32_e32 v103, v80
	v_exp_f32_e32 v107, v64
	v_exp_f32_e32 v109, v81
	v_exp_f32_e32 v65, v65
	v_exp_f32_e32 v121, v66
	v_add_f32_e32 v66, v109, v103
	v_add_f32_e32 v80, v65, v107
	v_add_f32_e32 v206, v121, v80
	v_exp_f32_e32 v207, v83
	v_add_u32_e32 v209, s7, v185
	v_exp_f32_e32 v64, v111
	v_exp_f32_e32 v111, v82
	v_exp_f32_e32 v208, v84
	ds_read_b128 v[80:83], v209 offset:18432
	ds_read_b128 v[196:199], v209 offset:18464
	ds_read_b128 v[200:203], v209 offset:23040
	v_exp_f32_e32 v212, v85
	v_exp_f32_e32 v213, v86
	v_cvt_pk_bf16_f32 v192, v177, v113
	v_exp_f32_e32 v177, v87
	v_cvt_pk_bf16_f32 v84, v103, v109
	v_exp_f32_e32 v109, v67
	v_add_f32_e32 v66, v111, v66
	v_cvt_pk_bf16_f32 v85, v111, v207
	v_exp_f32_e32 v111, v68
	v_cvt_pk_bf16_f32 v195, v181, v176
	v_exp_f32_e32 v181, v88
	v_cvt_pk_bf16_f32 v194, v99, v117
	v_exp_f32_e32 v117, v89
	v_cvt_pk_bf16_f32 v193, v179, v115
	v_cvt_pk_bf16_f32 v86, v208, v212
	v_cvt_pk_bf16_f32 v87, v213, v177
	v_exp_f32_e32 v99, v90
	s_waitcnt lgkmcnt(2)
	v_mfma_f32_32x32x16_bf16 v[48:63], v[80:83], v[192:195], v[48:63]
	v_exp_f32_e32 v105, v91
	v_exp_f32_e32 v119, v92
	v_exp_f32_e32 v125, v93
	v_mfma_f32_32x32x16_bf16 v[16:31], v[80:83], v[84:87], v[16:31]
	ds_read_b128 v[80:83], v209 offset:23072
	v_exp_f32_e32 v123, v94
	v_exp_f32_e32 v92, v69
	v_exp_f32_e32 v127, v95
	s_waitcnt lgkmcnt(1)
; __device__ __forceinline__ unsigned pk2(float lo, float hi) { f32x2_t v = {lo, hi}; bf16x2_t b = __builtin_convertvector(v, bf16x2_t); return __builtin_bit_cast(unsigned, b); }
; __device__ __forceinline__ float fexp2(float x) { return __builtin_amdgcn_exp2f(x); }
; #define MFMA(a, b, c) __builtin_amdgcn_mfma_f32_32x32x16_bf16((a), (b), (c), 0, 0, 0)
; template <int DQK, int DV>
; __device__ __forceinline__ void attn_pass2(const bf16_t* __restrict__ qh, const bf16_t* __restrict__ kh, const bf16_t* __restrict__ vth, int q0, char* smem, f32x16 (&o)[2][DV / 32], float kmax, int wvp) {
;     ...
;     for (int qb = 0; qb < 2; ++qb) {
;       float rs0 = 0.f, rs1 = 0.f;
; #pragma unroll
;       for (int i = 0; i < 16; ++i) { s[qb][0][i] = fexp2(s[qb][0][i] - mref[qb]); s[qb][1][i] = fexp2(s[qb][1][i] - mref[qb]); rs0 += s[qb][0][i]; rs1 += s[qb][1][i]; }
;       l_run[qb] += rs0 + rs1;
;     }
;     const char* vb0 = sV + cur * VSB + vofs;
; #pragma unroll
;     for (int kb = 0; kb < 2; ++kb)
; #pragma unroll
;       for (int s2 = 0; s2 < 2; ++s2) {
;         bf16x8 pq[2];
; #pragma unroll
;         for (int qb = 0; qb < 2; ++qb) {
;           u32x4 w;
;           w.x = pk2(s[qb][kb][8 * s2 + 0], s[qb][kb][8 * s2 + 1]); w.y = pk2(s[qb][kb][8 * s2 + 2], s[qb][kb][8 * s2 + 3]);
;           w.z = pk2(s[qb][kb][8 * s2 + 4], s[qb][kb][8 * s2 + 5]); w.w = pk2(s[qb][kb][8 * s2 + 6], s[qb][kb][8 * s2 + 7]);
;           pq[qb] = __builtin_bit_cast(bf16x8, w);
;         }
; #pragma unroll
;         for (int eb = 0; eb < NEB; ++eb) {
;           const bf16x8 a = *(const bf16x8*)(vb0 + eb * 32 * VP + (32 * kb + 16 * s2) * 2);
; #pragma unroll
;           for (int qb = 0; qb < 2; ++qb) o[qb][eb] = MFMA(a, pq[qb], o[qb][eb]);
;         }
;       }
;   }
	v_mfma_f32_32x32x16_bf16 v[0:15], v[200:203], v[84:87], v[0:15]
	v_exp_f32_e32 v93, v70
	v_add_f32_e32 v66, v207, v66
	v_add_f32_e32 v67, v109, v206
	v_add_f32_e32 v66, v208, v66
	v_add_f32_e32 v67, v111, v67
	v_add_f32_e32 v66, v212, v66
	v_add_f32_e32 v67, v92, v67
	v_mfma_f32_32x32x16_bf16 v[32:47], v[200:203], v[192:195], v[32:47]
	v_cvt_pk_bf16_f32 v84, v180, v116
	v_cvt_pk_bf16_f32 v85, v98, v104
	v_cvt_pk_bf16_f32 v86, v118, v124
	v_cvt_pk_bf16_f32 v87, v122, v126
	v_cvt_pk_bf16_f32 v88, v181, v117
	v_cvt_pk_bf16_f32 v89, v99, v105
	v_cvt_pk_bf16_f32 v90, v119, v125
	v_cvt_pk_bf16_f32 v91, v123, v127
	v_add_f32_e32 v113, v213, v66
	v_add_f32_e32 v103, v93, v67
	ds_read_b128 v[66:69], v209 offset:18496
	v_mfma_f32_32x32x16_bf16 v[48:63], v[196:199], v[84:87], v[48:63]
	v_exp_f32_e32 v179, v71
	v_mov_b32_e32 v70, v72
	v_exp_f32_e32 v115, v73
	v_cvt_pk_bf16_f32 v71, v121, v109
	v_cvt_pk_bf16_f32 v72, v111, v92
	v_cvt_pk_bf16_f32 v73, v93, v179
	v_mfma_f32_32x32x16_bf16 v[16:31], v[196:199], v[88:91], v[16:31]
	v_lshl_add_u64 v[170:171], v[170:171], 0, s[52:53]
	s_cmpk_lg_i32 s6, 0x80
	v_lshl_add_u64 v[172:173], v[172:173], 0, s[54:55]
	s_waitcnt lgkmcnt(1)
	v_mfma_f32_32x32x16_bf16 v[0:15], v[80:83], v[88:91], v[0:15]
	ds_read_b128 v[88:91], v209 offset:23104
	v_mfma_f32_32x32x16_bf16 v[32:47], v[80:83], v[84:87], v[32:47]
	v_cvt_pk_bf16_f32 v80, v186, v97
	v_exp_f32_e32 v97, v70
	v_cvt_pk_bf16_f32 v70, v107, v65
	v_cvt_pk_bf16_f32 v81, v187, v190
	v_cvt_pk_bf16_f32 v82, v204, v101
	v_cvt_pk_bf16_f32 v83, v205, v178
	v_exp_f32_e32 v101, v74
	ds_read_b128 v[84:87], v209 offset:18528
	s_waitcnt lgkmcnt(2)
	v_mfma_f32_32x32x16_bf16 v[48:63], v[66:69], v[80:83], v[48:63]
	v_exp_f32_e32 v107, v75
	v_exp_f32_e32 v121, v76
	v_exp_f32_e32 v109, v77
	v_exp_f32_e32 v111, v78
	v_mfma_f32_32x32x16_bf16 v[16:31], v[66:69], v[70:73], v[16:31]
	ds_read_b128 v[66:69], v209 offset:23136
	v_exp_f32_e32 v65, v79
	v_add_f32_e32 v74, v178, v102
	v_add_f32_e32 v75, v179, v103
	s_nop 0
	v_add_f32_e32 v74, v96, v74
	v_add_f32_e32 v75, v97, v75
	s_waitcnt lgkmcnt(2)
	v_mfma_f32_32x32x16_bf16 v[32:47], v[88:91], v[80:83], v[32:47]
	v_add_f32_e64 v80, v114, v74
	v_add_f32_e64 v81, v115, v75
	v_cvt_pk_bf16_f32 v74, v97, v115
	v_cvt_pk_bf16_f32 v75, v101, v107
	v_add_f32_e64 v80, v100, v80
	v_add_f32_e64 v81, v101, v81
	v_add_f32_e32 v80, v106, v80
	v_add_f32_e32 v81, v107, v81
	v_mfma_f32_32x32x16_bf16 v[0:15], v[88:91], v[70:73], v[0:15]
	v_add_f32_e64 v70, v176, v112
	v_add_f32_e64 v71, v177, v113
	v_cvt_pk_bf16_f32 v72, v120, v108
	v_add_f32_e64 v76, v180, v70
	v_add_f32_e64 v77, v181, v71
	v_cvt_pk_bf16_f32 v70, v96, v114
	v_cvt_pk_bf16_f32 v71, v100, v106
	v_cvt_pk_bf16_f32 v73, v110, v64
	v_add_f32_e32 v78, v116, v76
	v_add_f32_e32 v79, v117, v77
	v_cvt_pk_bf16_f32 v76, v121, v109
	v_cvt_pk_bf16_f32 v77, v111, v65
	s_waitcnt lgkmcnt(1)
	v_mfma_f32_32x32x16_bf16 v[48:63], v[84:87], v[70:73], v[48:63]
	v_add_f32_e64 v78, v98, v78
	v_add_f32_e64 v79, v99, v79
	v_add_f32_e64 v80, v120, v80
	v_add_f32_e64 v81, v121, v81
	v_add_f32_e64 v78, v104, v78
	v_add_f32_e64 v79, v105, v79
	v_add_f32_e32 v78, v118, v78
	v_add_f32_e32 v79, v119, v79
	s_nop 0
	v_add_f32_e32 v78, v124, v78
	v_add_f32_e32 v79, v125, v79
	v_mfma_f32_32x32x16_bf16 v[16:31], v[84:87], v[74:77], v[16:31]
	s_waitcnt lgkmcnt(0)
	v_mfma_f32_32x32x16_bf16 v[32:47], v[66:69], v[70:73], v[32:47]
	v_add_f32_e64 v70, v108, v80
	v_add_f32_e64 v71, v109, v81
	v_add_f32_e64 v72, v122, v78
	v_add_f32_e64 v73, v123, v79
	v_add_f32_e64 v70, v110, v70
	v_add_f32_e64 v71, v111, v71
	v_add_f32_e32 v72, v126, v72
	v_add_f32_e32 v73, v127, v73
	v_add_f32_e32 v64, v64, v70
	v_add_f32_e32 v65, v65, v71
	s_nop 0
	v_add_f32_e32 v64, v72, v64
	v_add_f32_e32 v65, v73, v65
	v_mfma_f32_32x32x16_bf16 v[0:15], v[66:69], v[74:77], v[0:15]
	v_add_f32_e64 v174, v174, v64
	v_add_f32_e64 v175, v175, v65
	s_cbranch_scc0 .LBB0_1433

; __device__ __forceinline__ unsigned pk2(float lo, float hi) { f32x2_t v = {lo, hi}; bf16x2_t b = __builtin_convertvector(v, bf16x2_t); return __builtin_bit_cast(unsigned, b); }
; __device__ __forceinline__ float fexp2(float x) { return __builtin_amdgcn_exp2f(x); }
; #define MFMA(a, b, c) __builtin_amdgcn_mfma_f32_32x32x16_bf16((a), (b), (c), 0, 0, 0)
; template <int DQK, int DV>
; __device__ __forceinline__ void attn_pass2(const bf16_t* __restrict__ qh, const bf16_t* __restrict__ kh, const bf16_t* __restrict__ vth, int q0, char* smem, f32x16 (&o)[2][DV / 32], float kmax, int wvp) {
;     ...
;     const char* kb0 = sK + cur * KSB + kofs;
; #pragma unroll
;     for (int ks = 0; ks < NKS; ++ks) {
;       const bf16x8 a0 = *(const bf16x8*)(kb0 + ks * 32), a1 = *(const bf16x8*)(kb0 + 32 * KP + ks * 32);
; #pragma unroll
;       for (int qb = 0; qb < 2; ++qb) {
;         if (ks == 0) {
;           f32x16 z;
; #pragma unroll
;           for (int i = 0; i < 16; ++i) z[i] = 0.f;
;           s[qb][0] = MFMA(a0, qf[qb][0], z); s[qb][1] = MFMA(a1, qf[qb][0], z);
;         } else { s[qb][0] = MFMA(a0, qf[qb][ks], s[qb][0]); s[qb][1] = MFMA(a1, qf[qb][ks], s[qb][1]); }
;       }
;     }
;     __builtin_amdgcn_sched_barrier(0);
; #pragma unroll
;     for (int qb = 0; qb < 2; ++qb) {
;       float rs0 = 0.f, rs1 = 0.f;
; #pragma unroll
;       for (int i = 0; i < 16; ++i) { s[qb][0][i] = fexp2(s[qb][0][i] - mref[qb]); s[qb][1][i] = fexp2(s[qb][1][i] - mref[qb]); rs0 += s[qb][0][i]; rs1 += s[qb][1][i]; }
;       l_run[qb] += rs0 + rs1;
;     }
;     const char* vb0 = sV + cur * VSB + vofs;
; #pragma unroll
;     for (int kb = 0; kb < 2; ++kb)
; #pragma unroll
;       for (int s2 = 0; s2 < 2; ++s2) {
;         bf16x8 pq[2];
; #pragma unroll
;         for (int qb = 0; qb < 2; ++qb) {
;           u32x4 w;
;           w.x = pk2(s[qb][kb][8 * s2 + 0], s[qb][kb][8 * s2 + 1]); w.y = pk2(s[qb][kb][8 * s2 + 2], s[qb][kb][8 * s2 + 3]);
;           w.z = pk2(s[qb][kb][8 * s2 + 4], s[qb][kb][8 * s2 + 5]); w.w = pk2(s[qb][kb][8 * s2 + 6], s[qb][kb][8 * s2 + 7]);
;           pq[qb] = __builtin_bit_cast(bf16x8, w);
.LBB0_1445:
	s_mul_i32 s8, s11, 0x3400
	v_add_u32_e32 v190, s8, v215
	ds_read_b128 v[64:67], v190
	ds_read_b128 v[202:205], v190 offset:32
	ds_read_b128 v[68:71], v190 offset:6656
	ds_read_b128 v[206:209], v190 offset:6688
	s_waitcnt lgkmcnt(3)
	v_mfma_f32_32x32x16_bf16 v[112:127], v[64:67], v[128:131], v[236:251]
	s_waitcnt lgkmcnt(1)
	v_mfma_f32_32x32x16_bf16 v[96:111], v[68:71], v[128:131], v[236:251]
	v_mfma_f32_32x32x16_bf16 v[80:95], v[64:67], v[152:155], v[236:251]
	v_mfma_f32_32x32x16_bf16 v[64:79], v[68:71], v[152:155], v[236:251]
	v_mfma_f32_32x32x16_bf16 v[112:127], v[202:205], v[132:135], v[112:127]
	s_waitcnt lgkmcnt(0)
	v_mfma_f32_32x32x16_bf16 v[96:111], v[206:209], v[132:135], v[96:111]
	v_mfma_f32_32x32x16_bf16 v[80:95], v[202:205], v[156:159], v[80:95]
	v_mfma_f32_32x32x16_bf16 v[64:79], v[206:209], v[156:159], v[64:79]
	ds_read_b128 v[202:205], v190 offset:64
	ds_read_b128 v[206:209], v190 offset:96
	ds_read_b128 v[218:221], v190 offset:6720
	ds_read_b128 v[222:225], v190 offset:6752
	s_waitcnt lgkmcnt(3)
	v_mfma_f32_32x32x16_bf16 v[112:127], v[202:205], v[136:139], v[112:127]
	s_waitcnt lgkmcnt(1)
	v_mfma_f32_32x32x16_bf16 v[96:111], v[218:221], v[136:139], v[96:111]
	v_mfma_f32_32x32x16_bf16 v[80:95], v[202:205], v[160:163], v[80:95]
	v_mfma_f32_32x32x16_bf16 v[64:79], v[218:221], v[160:163], v[64:79]
	v_mfma_f32_32x32x16_bf16 v[112:127], v[206:209], v[140:143], v[112:127]
	s_waitcnt lgkmcnt(0)
	v_mfma_f32_32x32x16_bf16 v[96:111], v[222:225], v[140:143], v[96:111]
	v_mfma_f32_32x32x16_bf16 v[80:95], v[206:209], v[164:167], v[80:95]
	ds_read_b128 v[202:205], v190 offset:128
	ds_read_b128 v[206:209], v190 offset:160
	v_mfma_f32_32x32x16_bf16 v[64:79], v[222:225], v[164:167], v[64:79]
	ds_read_b128 v[218:221], v190 offset:6784
	ds_read_b128 v[222:225], v190 offset:6816
	s_waitcnt lgkmcnt(3)
	v_mfma_f32_32x32x16_bf16 v[112:127], v[202:205], v[144:147], v[112:127]
	s_waitcnt lgkmcnt(1)
	v_mfma_f32_32x32x16_bf16 v[96:111], v[218:221], v[144:147], v[96:111]
	v_mfma_f32_32x32x16_bf16 v[80:95], v[202:205], v[168:171], v[80:95]
	v_mfma_f32_32x32x16_bf16 v[64:79], v[218:221], v[168:171], v[64:79]
	v_mfma_f32_32x32x16_bf16 v[112:127], v[206:209], v[148:151], v[112:127]
	s_waitcnt lgkmcnt(0)
	v_mfma_f32_32x32x16_bf16 v[96:111], v[222:225], v[148:151], v[96:111]
	v_mfma_f32_32x32x16_bf16 v[80:95], v[206:209], v[172:175], v[80:95]
	v_mfma_f32_32x32x16_bf16 v[64:79], v[222:225], v[172:175], v[64:79]
	s_nop 9
	v_exp_f32_e32 v96, v96
	v_exp_f32_e32 v112, v112
	v_exp_f32_e32 v208, v97
	v_exp_f32_e32 v204, v113
	v_exp_f32_e32 v227, v99
	v_exp_f32_e32 v114, v114
	v_exp_f32_e32 v116, v116
	v_exp_f32_e32 v217, v98
	v_exp_f32_e32 v100, v100
	v_add_f32_e32 v98, v208, v96
	v_exp_f32_e32 v202, v117
	v_add_f32_e32 v97, v204, v112
	v_exp_f32_e32 v190, v115
	v_exp_f32_e32 v228, v101
	v_exp_f32_e32 v118, v118
	v_add_f32_e32 v98, v217, v98
	v_exp_f32_e32 v229, v102
	v_add_f32_e32 v97, v114, v97
	v_add_f32_e32 v98, v227, v98
	v_add_f32_e32 v97, v190, v97
	v_add_f32_e32 v98, v100, v98
	v_add_f32_e32 v97, v116, v97
	v_add_f32_e32 v98, v228, v98
	v_add_f32_e32 v97, v202, v97
	v_add_f32_e32 v113, v229, v98
	v_add_f32_e32 v115, v118, v97
	v_exp_f32_e32 v203, v119
	v_exp_f32_e32 v119, v121
	v_exp_f32_e32 v117, v105
	v_exp_f32_e32 v99, v122
	v_exp_f32_e32 v101, v106
	v_exp_f32_e32 v205, v103
	v_exp_f32_e32 v103, v123
	v_exp_f32_e32 v105, v107
	v_exp_f32_e32 v107, v124
	v_exp_f32_e32 v121, v108
	v_exp_f32_e32 v125, v125
	v_exp_f32_e32 v109, v109
	v_exp_f32_e32 v123, v126
	v_exp_f32_e32 v209, v110
	v_exp_f32_e32 v127, v127
	v_exp_f32_e32 v98, v80
	v_exp_f32_e32 v102, v81
	v_exp_f32_e32 v108, v65
	v_exp_f32_e32 v207, v120
	v_exp_f32_e32 v97, v104
	v_exp_f32_e32 v104, v64
	v_exp_f32_e32 v106, v82
	v_exp_f32_e32 v111, v111
	v_exp_f32_e32 v110, v66
	v_add_f32_e32 v64, v102, v98
	v_add_f32_e32 v120, v106, v64
	s_mulk_i32 s11, 0x2400
	v_add_f32_e32 v65, v108, v104
	v_exp_f32_e32 v231, v83
	v_add_u32_e32 v233, s11, v216
	v_add_f32_e32 v230, v110, v65
	v_mov_b32_e32 v122, v67
	v_exp_f32_e32 v232, v84
	ds_read_b128 v[64:67], v233 offset:26624
	ds_read_b128 v[218:221], v233 offset:26656
	v_exp_f32_e32 v234, v85
	ds_read_b128 v[222:225], v233 offset:31232
	v_exp_f32_e32 v235, v86
	v_cvt_pk_bf16_f32 v82, v116, v202
	v_exp_f32_e32 v202, v87
	v_cvt_pk_bf16_f32 v80, v112, v204
	v_cvt_pk_bf16_f32 v81, v114, v190
	v_cvt_pk_bf16_f32 v83, v118, v203
	v_cvt_pk_bf16_f32 v84, v98, v102
	v_cvt_pk_bf16_f32 v85, v106, v231
	v_cvt_pk_bf16_f32 v86, v232, v234
	v_cvt_pk_bf16_f32 v87, v235, v202
	s_waitcnt lgkmcnt(2)
; __device__ __forceinline__ unsigned pk2(float lo, float hi) { f32x2_t v = {lo, hi}; bf16x2_t b = __builtin_convertvector(v, bf16x2_t); return __builtin_bit_cast(unsigned, b); }
; __device__ __forceinline__ float fexp2(float x) { return __builtin_amdgcn_exp2f(x); }
; #define MFMA(a, b, c) __builtin_amdgcn_mfma_f32_32x32x16_bf16((a), (b), (c), 0, 0, 0)
; template <int DQK, int DV>
; __device__ __forceinline__ void attn_pass2(const bf16_t* __restrict__ qh, const bf16_t* __restrict__ kh, const bf16_t* __restrict__ vth, int q0, char* smem, f32x16 (&o)[2][DV / 32], float kmax, int wvp) {
;     ...
;     for (int qb = 0; qb < 2; ++qb) {
;       float rs0 = 0.f, rs1 = 0.f;
; #pragma unroll
;       for (int i = 0; i < 16; ++i) { s[qb][0][i] = fexp2(s[qb][0][i] - mref[qb]); s[qb][1][i] = fexp2(s[qb][1][i] - mref[qb]); rs0 += s[qb][0][i]; rs1 += s[qb][1][i]; }
;       l_run[qb] += rs0 + rs1;
;     }
;     const char* vb0 = sV + cur * VSB + vofs;
; #pragma unroll
;     for (int kb = 0; kb < 2; ++kb)
; #pragma unroll
;       for (int s2 = 0; s2 < 2; ++s2) {
;         bf16x8 pq[2];
; #pragma unroll
;         for (int qb = 0; qb < 2; ++qb) {
;           u32x4 w;
;           w.x = pk2(s[qb][kb][8 * s2 + 0], s[qb][kb][8 * s2 + 1]); w.y = pk2(s[qb][kb][8 * s2 + 2], s[qb][kb][8 * s2 + 3]);
;           w.z = pk2(s[qb][kb][8 * s2 + 4], s[qb][kb][8 * s2 + 5]); w.w = pk2(s[qb][kb][8 * s2 + 6], s[qb][kb][8 * s2 + 7]);
;           pq[qb] = __builtin_bit_cast(bf16x8, w);
;         }
; #pragma unroll
;         for (int eb = 0; eb < NEB; ++eb) {
;           const bf16x8 a = *(const bf16x8*)(vb0 + eb * 32 * VP + (32 * kb + 16 * s2) * 2);
; #pragma unroll
;           for (int qb = 0; qb < 2; ++qb) o[qb][eb] = MFMA(a, pq[qb], o[qb][eb]);
;         }
;       }
;   }
	v_mfma_f32_32x32x16_bf16 v[48:63], v[64:67], v[80:83], v[48:63]
	v_exp_f32_e32 v116, v122
	s_add_u32 s6, s6, 0x3000
	s_addc_u32 s7, s7, 0
	s_add_i32 s10, s10, 1
	v_mfma_f32_32x32x16_bf16 v[16:31], v[64:67], v[84:87], v[16:31]
	v_exp_f32_e32 v190, v68
	v_exp_f32_e32 v206, v88
	ds_read_b128 v[64:67], v233 offset:31264
	v_exp_f32_e32 v118, v89
	s_waitcnt lgkmcnt(1)
	v_mfma_f32_32x32x16_bf16 v[32:47], v[222:225], v[80:83], v[32:47]
	v_exp_f32_e32 v98, v90
	v_exp_f32_e32 v102, v91
	v_exp_f32_e32 v106, v92
	v_exp_f32_e32 v124, v93
	v_mfma_f32_32x32x16_bf16 v[0:15], v[222:225], v[84:87], v[0:15]
	v_exp_f32_e32 v122, v94
	v_exp_f32_e32 v89, v69
	v_exp_f32_e32 v126, v95
	v_exp_f32_e32 v90, v70
	v_cvt_pk_bf16_f32 v80, v207, v119
	v_cvt_pk_bf16_f32 v81, v99, v103
	v_cvt_pk_bf16_f32 v82, v107, v125
	v_cvt_pk_bf16_f32 v83, v123, v127
	v_add_f32_e32 v68, v231, v120
	v_add_f32_e32 v88, v116, v230
	v_mfma_f32_32x32x16_bf16 v[48:63], v[218:221], v[80:83], v[48:63]
	v_add_f32_e32 v68, v232, v68
	v_add_f32_e32 v88, v190, v88
	v_add_f32_e32 v68, v234, v68
	v_add_f32_e32 v69, v89, v88
	v_cvt_pk_bf16_f32 v84, v206, v118
	v_cvt_pk_bf16_f32 v85, v98, v102
	v_cvt_pk_bf16_f32 v86, v106, v124
	s_waitcnt lgkmcnt(0)
	v_mfma_f32_32x32x16_bf16 v[32:47], v[64:67], v[80:83], v[32:47]
	v_exp_f32_e32 v204, v71
	v_cvt_pk_bf16_f32 v87, v122, v126
	v_add_f32_e32 v114, v235, v68
	v_add_f32_e32 v112, v90, v69
	ds_read_b128 v[68:71], v233 offset:26688
	ds_read_b128 v[80:83], v233 offset:26720
	v_mfma_f32_32x32x16_bf16 v[16:31], v[218:221], v[84:87], v[16:31]
	s_cmp_lg_u32 s6, 0x180000
	v_lshl_add_u64 v[194:195], v[194:195], 0, s[54:55]
	v_mfma_f32_32x32x16_bf16 v[0:15], v[64:67], v[84:87], v[0:15]
	v_cvt_pk_bf16_f32 v86, v190, v89
	v_cvt_pk_bf16_f32 v87, v90, v204
	ds_read_b128 v[88:91], v233 offset:31296
	v_cvt_pk_bf16_f32 v64, v96, v208
	v_cvt_pk_bf16_f32 v65, v217, v227
	v_cvt_pk_bf16_f32 v66, v100, v228
	v_cvt_pk_bf16_f32 v67, v229, v205
	v_cvt_pk_bf16_f32 v84, v104, v108
	v_cvt_pk_bf16_f32 v85, v110, v116
	s_waitcnt lgkmcnt(2)
	v_mfma_f32_32x32x16_bf16 v[48:63], v[68:71], v[64:67], v[48:63]
	v_exp_f32_e32 v96, v72
	v_exp_f32_e32 v116, v73
	v_exp_f32_e32 v120, v76
	v_add_f32_e32 v72, v204, v112
	v_add_f32_e32 v73, v205, v113
	v_mfma_f32_32x32x16_bf16 v[16:31], v[68:71], v[84:87], v[16:31]
	v_exp_f32_e32 v100, v74
	v_exp_f32_e32 v104, v75
	ds_read_b128 v[68:71], v233 offset:31328
	v_add_f32_e32 v72, v96, v72
	v_add_f32_e32 v73, v97, v73
	s_waitcnt lgkmcnt(1)
	v_mfma_f32_32x32x16_bf16 v[32:47], v[88:91], v[64:67], v[32:47]
	v_exp_f32_e32 v108, v77
	v_exp_f32_e32 v208, v78
	v_exp_f32_e32 v110, v79
	v_add_f32_e32 v64, v202, v114
	v_add_f32_e32 v65, v203, v115
	v_mfma_f32_32x32x16_bf16 v[0:15], v[88:91], v[84:87], v[0:15]
	v_add_f32_e64 v74, v206, v64
	v_add_f32_e64 v75, v207, v65
	v_cvt_pk_bf16_f32 v64, v97, v117
	v_cvt_pk_bf16_f32 v65, v101, v105
	v_cvt_pk_bf16_f32 v66, v121, v109
	v_cvt_pk_bf16_f32 v67, v209, v111
	v_add_f32_e32 v76, v118, v74
	v_add_f32_e32 v77, v119, v75
	v_add_f32_e32 v78, v116, v72
	v_add_f32_e32 v79, v117, v73
	v_cvt_pk_bf16_f32 v72, v96, v116
	v_cvt_pk_bf16_f32 v73, v100, v104
	v_cvt_pk_bf16_f32 v74, v120, v108
	v_cvt_pk_bf16_f32 v75, v208, v110
	v_mfma_f32_32x32x16_bf16 v[48:63], v[80:83], v[64:67], v[48:63]
	v_add_f32_e64 v76, v98, v76
	v_add_f32_e64 v77, v99, v77
	v_add_f32_e64 v78, v100, v78
	v_add_f32_e64 v79, v101, v79
	v_add_f32_e64 v76, v102, v76
	v_add_f32_e64 v77, v103, v77
	v_add_f32_e32 v78, v104, v78
	v_add_f32_e32 v79, v105, v79
	v_add_f32_e32 v76, v106, v76
	v_add_f32_e32 v77, v107, v77
	v_add_f32_e32 v78, v120, v78
	v_add_f32_e32 v79, v121, v79
	v_add_f32_e32 v76, v124, v76
	v_add_f32_e32 v77, v125, v77
	v_mfma_f32_32x32x16_bf16 v[16:31], v[80:83], v[72:75], v[16:31]
	s_waitcnt lgkmcnt(0)
	v_mfma_f32_32x32x16_bf16 v[32:47], v[68:71], v[64:67], v[32:47]
	v_add_f32_e64 v64, v108, v78
	v_add_f32_e64 v65, v109, v79
	v_add_f32_e64 v66, v122, v76
	v_add_f32_e64 v67, v123, v77
	v_add_f32_e64 v64, v208, v64
	v_add_f32_e64 v65, v209, v65
	v_add_f32_e32 v66, v126, v66
	v_add_f32_e32 v67, v127, v67
	v_add_f32_e32 v64, v110, v64
	v_add_f32_e32 v65, v111, v65
	s_nop 0
	v_add_f32_e32 v64, v66, v64
	v_add_f32_e32 v65, v67, v65
	v_mfma_f32_32x32x16_bf16 v[0:15], v[68:71], v[72:75], v[0:15]
	v_add_f32_e64 v200, v200, v64
	v_add_f32_e64 v201, v201, v65
	s_cbranch_scc0 .LBB0_1425
